# attention: next-supertile K/V register prefetch loads issued 2 per sub-tile iteration instead of one 8-load clump after the barrier (plus mLSTM finalize rewrite)
# speedup vs baseline: 1.0056x; 1.0056x over previous
.LBB0_148:
	s_bitcmp1_b32 s4, 0
	s_cselect_b32 s11, 0x11800, 0
	s_add_i32 s14, s11, 0
	v_add_u32_e32 v90, s14, v199
	v_add3_u32 v91, s14, v96, v205
	v_add_u32_e32 v7, v90, v218
	v_add_u32_e32 v2, v90, v219
	v_add_u32_e32 v11, v90, v220
	v_add_u32_e32 v1, v90, v221
	s_waitcnt vmcnt(0)
	ds_write_b128 v91, v[106:109]
	ds_write_b128 v7, v[110:113] offset:36864
	ds_write_b128 v91, v[114:117] offset:9216
	ds_write_b128 v2, v[118:121] offset:36864
	ds_write_b128 v91, v[122:125] offset:18432
	ds_write_b128 v11, v[126:129] offset:36864
	ds_write_b128 v91, v[130:133] offset:27648
	ds_write_b128 v1, v[134:137] offset:36864
	s_and_saveexec_b64 s[12:13], s[42:43]
	v_add_u32_e32 v3, s14, v203
	v_add_u32_e32 v3, 0x11400, v3
	ds_write_b32 v3, v189
	s_or_b64 exec, exec, s[12:13]
	s_waitcnt lgkmcnt(0)
	s_barrier
	s_cmp_eq_u32 s2, s4
	s_cselect_b64 s[12:13], -1, 0
	s_mov_b32 s14, 0
	s_and_b64 vcc, exec, s[12:13]
	s_cbranch_vccnz .LBB0_154
	s_sub_i32 s16, s2, s4
	s_lshl_b32 s15, s16, 8
	s_add_i32 s36, s15, 0xffffff00
	v_lshl_add_u32 v1, s36, 1, v204
	v_lshl_add_u32 v2, s36, 11, v174
	s_lshl_b32 s16, s16, 19
	v_subrev_u32_e32 v2, s74, v2
	v_add_u32_e32 v3, v1, v192
	s_add_i32 s17, s16, 0xfffa0000
	v_subrev_u32_e32 v3, s74, v3
	v_mov_b32_e32 v106, v2
	v_mov_b32_e32 v110, v3
	v_add_u32_e32 v2, s17, v174
	v_subrev_u32_e32 v2, s74, v2
	v_add_u32_e32 v3, v1, v194
	s_add_i32 s17, s16, 0xfffc0000
	v_subrev_u32_e32 v3, s74, v3
	v_mov_b32_e32 v114, v2
	v_mov_b32_e32 v118, v3
	v_add_u32_e32 v2, s17, v174
	v_subrev_u32_e32 v2, s74, v2
	v_add_u32_e32 v3, v1, v196
	s_add_i32 s16, s16, 0xfffe0000
	v_subrev_u32_e32 v3, s74, v3
	v_mov_b32_e32 v122, v2
	v_mov_b32_e32 v126, v3
	v_add_u32_e32 v2, s16, v174
	v_subrev_u32_e32 v2, s74, v2
	v_add_u32_e32 v1, v1, v198
	v_subrev_u32_e32 v1, s74, v1
	v_mov_b32_e32 v130, v2
	v_mov_b32_e32 v134, v1
	s_and_saveexec_b64 s[44:45], s[42:43]
	s_cbranch_execz .LBB0_153
	v_lshl_add_u64 v[2:3], s[36:37], 2, v[206:207]
	global_load_dword v189, v[2:3], off sc1

.LBB0_158:
	s_cmp_eq_u32 s2, s4
	s_cbranch_scc1 .Lat_done
	s_cmpk_eq_i32 s14, 0
	s_cbranch_scc0 .Lat_1
	buffer_load_dwordx4 v[106:109], v106, s[76:79], 0 offen sc1
	buffer_load_dwordx4 v[110:113], v110, s[76:79], 0 offen sc1
	s_branch .Lat_done
.Lat_1:
	s_cmpk_eq_i32 s14, 0xffc0
	s_cbranch_scc0 .Lat_2
	buffer_load_dwordx4 v[114:117], v114, s[76:79], 0 offen sc1
	buffer_load_dwordx4 v[118:121], v118, s[76:79], 0 offen sc1
	s_branch .Lat_done
.Lat_2:
	s_cmpk_eq_i32 s14, 0xff80
	s_cbranch_scc0 .Lat_3
	buffer_load_dwordx4 v[122:125], v122, s[76:79], 0 offen sc1
	buffer_load_dwordx4 v[126:129], v126, s[76:79], 0 offen sc1
	s_branch .Lat_done
.Lat_3:
	buffer_load_dwordx4 v[130:133], v130, s[76:79], 0 offen sc1
	buffer_load_dwordx4 v[134:137], v134, s[76:79], 0 offen sc1
